# static priority variant: s_setprio 1 for waves 0-3 (older half) at kernel start, per-cluster flips deleted
# baseline (speedup 1.0000x reference)
; #define LAS __attribute__((address_space(3)))
; __global__ void __launch_bounds__(NTH) fwd_megakernel(Params p) {
;     ...
;   cg::grid_group grid = cg::this_grid();
;   extern __shared__ __attribute__((aligned(16))) char dyn_lds[];
;   volatile LAS unsigned* xst = (volatile LAS unsigned*)((LAS unsigned char*)dyn_lds + NSA_LDS);
;   if (threadIdx.x == 0) { xst[0] = 0u; xst[1] = 0u; xst[2] = 0u; xst[3] = 0u; }
;   __syncthreads();
;   const XcdBarrier xb = xcd_barrier_post((unsigned*)(p.ws + A_BAR), xst);
.LBB0_6:
	v_readfirstlane_b32 s100, v199
	s_nop 3
	s_lshr_b32 s100, s100, 6
	s_cmp_ge_u32 s100, 4
	s_cbranch_scc1 .Lprio_done
	s_setprio 1
